# fused resid+norm epilogue: batch the 12 g/scale/shift loads (both instances), norm0 hand loop, sc1 H stores
# speedup vs baseline: 1.0708x; 1.0071x over previous
.LBB0_48:
	v_readfirstlane_b32 s52, v70
	v_readfirstlane_b32 s53, v71
	v_readfirstlane_b32 s54, v34
	v_readfirstlane_b32 s55, v35
	s_add_u32 s56, s22, 0x5a00000
	s_addc_u32 s57, s23, 0
	s_lshl_b32 s31, s24, 11
	s_add_u32 s56, s56, s31
	s_addc_u32 s57, s57, 0
	s_lshl_b32 s48, s24, 12
	v_lshlrev_b32_e32 v82, 5, v244
	v_lshlrev_b32_e32 v83, 4, v244
	global_load_dwordx4 v[84:87], v82, s[52:53]
	global_load_dwordx4 v[88:91], v82, s[52:53] offset:16
	global_load_dwordx4 v[92:95], v82, s[52:53] offset:2048
	global_load_dwordx4 v[96:99], v82, s[52:53] offset:2064
	s_add_u32 s40, s97, s48
	s_addc_u32 s41, s3, 0
	s_add_u32 s42, s54, 0x0
	s_addc_u32 s43, s55, 0
	s_add_u32 s44, s42, 0x1000
	s_addc_u32 s45, s43, 0
	global_load_dwordx4 v[0:3], v82, s[40:41]
	global_load_dwordx4 v[4:7], v82, s[40:41] offset:16
	global_load_dwordx4 v[8:11], v82, s[40:41] offset:2048
	global_load_dwordx4 v[12:15], v82, s[40:41] offset:2064
	global_load_dwordx4 v[16:19], v82, s[44:45]
	global_load_dwordx4 v[20:23], v82, s[44:45] offset:16
	global_load_dwordx4 v[24:27], v82, s[44:45] offset:2048
	global_load_dwordx4 v[28:31], v82, s[44:45] offset:2064
	global_load_dwordx4 v[38:41], v82, s[42:43]
	global_load_dwordx4 v[42:45], v82, s[42:43] offset:16
	global_load_dwordx4 v[46:49], v82, s[42:43] offset:2048
	global_load_dwordx4 v[50:53], v82, s[42:43] offset:2064
	s_add_u32 s40, s97, s48
	s_addc_u32 s41, s3, 0
	s_add_u32 s40, s40, 0x800000
	s_addc_u32 s41, s41, 0
	s_add_u32 s42, s54, 0x9000
	s_addc_u32 s43, s55, 0
	s_add_u32 s44, s42, 0x1000
	s_addc_u32 s45, s43, 0
	global_load_dwordx4 v[100:103], v82, s[40:41]
	global_load_dwordx4 v[104:107], v82, s[40:41] offset:16
	global_load_dwordx4 v[108:111], v82, s[40:41] offset:2048
	global_load_dwordx4 v[112:115], v82, s[40:41] offset:2064
	global_load_dwordx4 v[116:119], v82, s[44:45]
	global_load_dwordx4 v[120:123], v82, s[44:45] offset:16
	global_load_dwordx4 v[124:127], v82, s[44:45] offset:2048
	global_load_dwordx4 v[128:131], v82, s[44:45] offset:2064
	global_load_dwordx4 v[132:135], v82, s[42:43]
	global_load_dwordx4 v[136:139], v82, s[42:43] offset:16
	global_load_dwordx4 v[140:143], v82, s[42:43] offset:2048
	global_load_dwordx4 v[144:147], v82, s[42:43] offset:2064
	s_waitcnt vmcnt(12)
	v_pk_mul_f32 v[54:55], v[0:1], v[0:1]
	v_pk_mul_f32 v[56:57], v[2:3], v[2:3]
	v_pk_fma_f32 v[54:55], v[4:5], v[4:5], v[54:55]
	v_pk_fma_f32 v[56:57], v[6:7], v[6:7], v[56:57]
	v_pk_fma_f32 v[54:55], v[8:9], v[8:9], v[54:55]
	v_pk_fma_f32 v[56:57], v[10:11], v[10:11], v[56:57]
	v_pk_fma_f32 v[54:55], v[12:13], v[12:13], v[54:55]
	v_pk_fma_f32 v[56:57], v[14:15], v[14:15], v[56:57]
	v_pk_add_f32 v[54:55], v[54:55], v[56:57]
	v_pk_fma_f32 v[16:17], v[84:85], v[16:17], v[84:85]
	v_add_f32_e32 v54, v54, v55
	v_pk_fma_f32 v[18:19], v[86:87], v[18:19], v[86:87]
	v_pk_fma_f32 v[20:21], v[88:89], v[20:21], v[88:89]
	v_add_f32_dpp v54, v54, v54 quad_perm:[1,0,3,2] row_mask:0xf bank_mask:0xf
	v_pk_fma_f32 v[22:23], v[90:91], v[22:23], v[90:91]
	v_pk_fma_f32 v[24:25], v[92:93], v[24:25], v[92:93]
	v_add_f32_dpp v54, v54, v54 quad_perm:[2,3,0,1] row_mask:0xf bank_mask:0xf
	v_pk_fma_f32 v[26:27], v[94:95], v[26:27], v[94:95]
	v_pk_fma_f32 v[28:29], v[96:97], v[28:29], v[96:97]
	v_add_f32_dpp v54, v54, v54 row_half_mirror row_mask:0xf bank_mask:0xf
	v_pk_fma_f32 v[30:31], v[98:99], v[30:31], v[98:99]
	s_nop 1
	v_add_f32_dpp v54, v54, v54 row_mirror row_mask:0xf bank_mask:0xf
	s_nop 0
	v_mov_b32_e32 v55, v54
	s_nop 1
	v_permlane16_swap_b32_e32 v54, v55
	s_nop 0
	v_add_f32_e32 v54, v54, v55
	s_nop 0
	v_mov_b32_e32 v55, v54
	s_nop 1
	v_permlane32_swap_b32_e32 v54, v55
	s_nop 0
	v_add_f32_e32 v54, v54, v55
	v_fmamk_f32 v54, v54, 0x3a800000, v227
	v_rsq_f32_e32 v54, v54
	s_nop 1
	v_pk_mul_f32 v[0:1], v[0:1], v[54:55] op_sel_hi:[1,0]
	v_pk_mul_f32 v[2:3], v[2:3], v[54:55] op_sel_hi:[1,0]
	v_pk_mul_f32 v[4:5], v[4:5], v[54:55] op_sel_hi:[1,0]
	v_pk_mul_f32 v[6:7], v[6:7], v[54:55] op_sel_hi:[1,0]
	v_pk_mul_f32 v[8:9], v[8:9], v[54:55] op_sel_hi:[1,0]
	v_pk_mul_f32 v[10:11], v[10:11], v[54:55] op_sel_hi:[1,0]
	v_pk_mul_f32 v[12:13], v[12:13], v[54:55] op_sel_hi:[1,0]
	v_pk_mul_f32 v[14:15], v[14:15], v[54:55] op_sel_hi:[1,0]
	v_pk_fma_f32 v[0:1], v[0:1], v[16:17], v[38:39]
	v_pk_fma_f32 v[2:3], v[2:3], v[18:19], v[40:41]
	v_pk_fma_f32 v[4:5], v[4:5], v[20:21], v[42:43]
	v_pk_fma_f32 v[6:7], v[6:7], v[22:23], v[44:45]
	v_pk_fma_f32 v[8:9], v[8:9], v[24:25], v[46:47]
	v_pk_fma_f32 v[10:11], v[10:11], v[26:27], v[48:49]
	v_pk_fma_f32 v[12:13], v[12:13], v[28:29], v[50:51]
	v_pk_fma_f32 v[14:15], v[14:15], v[30:31], v[52:53]
	v_cvt_pk_bf16_f32 v0, v0, v1
	v_cvt_pk_bf16_f32 v1, v2, v3
	v_cvt_pk_bf16_f32 v2, v4, v5
	v_cvt_pk_bf16_f32 v3, v6, v7
	v_cvt_pk_bf16_f32 v4, v8, v9
	v_cvt_pk_bf16_f32 v5, v10, v11
	v_cvt_pk_bf16_f32 v6, v12, v13
	v_cvt_pk_bf16_f32 v7, v14, v15
	global_store_dwordx4 v83, v[0:3], s[56:57]
	global_store_dwordx4 v83, v[4:7], s[56:57] offset:1024
	s_add_u32 s40, s97, s48
	s_addc_u32 s41, s3, 0
	s_add_u32 s40, s40, 0x1000000
	s_addc_u32 s41, s41, 0
	s_add_u32 s42, s54, 0x12000
	s_addc_u32 s43, s55, 0
	s_add_u32 s44, s42, 0x1000
	s_addc_u32 s45, s43, 0
	global_load_dwordx4 v[0:3], v82, s[40:41]
	global_load_dwordx4 v[4:7], v82, s[40:41] offset:16
	global_load_dwordx4 v[8:11], v82, s[40:41] offset:2048
	global_load_dwordx4 v[12:15], v82, s[40:41] offset:2064
	global_load_dwordx4 v[16:19], v82, s[44:45]
	global_load_dwordx4 v[20:23], v82, s[44:45] offset:16
	global_load_dwordx4 v[24:27], v82, s[44:45] offset:2048
	global_load_dwordx4 v[28:31], v82, s[44:45] offset:2064
	global_load_dwordx4 v[38:41], v82, s[42:43]
	global_load_dwordx4 v[42:45], v82, s[42:43] offset:16
	global_load_dwordx4 v[46:49], v82, s[42:43] offset:2048
	global_load_dwordx4 v[50:53], v82, s[42:43] offset:2064
	s_waitcnt vmcnt(12)
	v_pk_mul_f32 v[54:55], v[100:101], v[100:101]
	v_pk_mul_f32 v[56:57], v[102:103], v[102:103]
	v_pk_fma_f32 v[54:55], v[104:105], v[104:105], v[54:55]
	v_pk_fma_f32 v[56:57], v[106:107], v[106:107], v[56:57]
	v_pk_fma_f32 v[54:55], v[108:109], v[108:109], v[54:55]
	v_pk_fma_f32 v[56:57], v[110:111], v[110:111], v[56:57]
	v_pk_fma_f32 v[54:55], v[112:113], v[112:113], v[54:55]
	v_pk_fma_f32 v[56:57], v[114:115], v[114:115], v[56:57]
	v_pk_add_f32 v[54:55], v[54:55], v[56:57]
	v_pk_fma_f32 v[116:117], v[84:85], v[116:117], v[84:85]
	v_add_f32_e32 v54, v54, v55
	v_pk_fma_f32 v[118:119], v[86:87], v[118:119], v[86:87]
	v_pk_fma_f32 v[120:121], v[88:89], v[120:121], v[88:89]
	v_add_f32_dpp v54, v54, v54 quad_perm:[1,0,3,2] row_mask:0xf bank_mask:0xf
	v_pk_fma_f32 v[122:123], v[90:91], v[122:123], v[90:91]
	v_pk_fma_f32 v[124:125], v[92:93], v[124:125], v[92:93]
	v_add_f32_dpp v54, v54, v54 quad_perm:[2,3,0,1] row_mask:0xf bank_mask:0xf
	v_pk_fma_f32 v[126:127], v[94:95], v[126:127], v[94:95]
	v_pk_fma_f32 v[128:129], v[96:97], v[128:129], v[96:97]
	v_add_f32_dpp v54, v54, v54 row_half_mirror row_mask:0xf bank_mask:0xf
	v_pk_fma_f32 v[130:131], v[98:99], v[130:131], v[98:99]
	s_nop 1
	v_add_f32_dpp v54, v54, v54 row_mirror row_mask:0xf bank_mask:0xf
	s_nop 0
	v_mov_b32_e32 v55, v54
	s_nop 1
	v_permlane16_swap_b32_e32 v54, v55
	s_nop 0
	v_add_f32_e32 v54, v54, v55
	s_nop 0
	v_mov_b32_e32 v55, v54
	s_nop 1
	v_permlane32_swap_b32_e32 v54, v55
	s_nop 0
	v_add_f32_e32 v54, v54, v55
	v_fmamk_f32 v54, v54, 0x3a800000, v227
	v_rsq_f32_e32 v54, v54
	s_nop 1
	v_pk_mul_f32 v[100:101], v[100:101], v[54:55] op_sel_hi:[1,0]
	v_pk_mul_f32 v[102:103], v[102:103], v[54:55] op_sel_hi:[1,0]
	v_pk_mul_f32 v[104:105], v[104:105], v[54:55] op_sel_hi:[1,0]
	v_pk_mul_f32 v[106:107], v[106:107], v[54:55] op_sel_hi:[1,0]
	v_pk_mul_f32 v[108:109], v[108:109], v[54:55] op_sel_hi:[1,0]
	v_pk_mul_f32 v[110:111], v[110:111], v[54:55] op_sel_hi:[1,0]
	v_pk_mul_f32 v[112:113], v[112:113], v[54:55] op_sel_hi:[1,0]
	v_pk_mul_f32 v[114:115], v[114:115], v[54:55] op_sel_hi:[1,0]
	v_pk_fma_f32 v[100:101], v[100:101], v[116:117], v[132:133]
	v_pk_fma_f32 v[102:103], v[102:103], v[118:119], v[134:135]
	v_pk_fma_f32 v[104:105], v[104:105], v[120:121], v[136:137]
	v_pk_fma_f32 v[106:107], v[106:107], v[122:123], v[138:139]
	v_pk_fma_f32 v[108:109], v[108:109], v[124:125], v[140:141]
	v_pk_fma_f32 v[110:111], v[110:111], v[126:127], v[142:143]
	v_pk_fma_f32 v[112:113], v[112:113], v[128:129], v[144:145]
	v_pk_fma_f32 v[114:115], v[114:115], v[130:131], v[146:147]
	v_cvt_pk_bf16_f32 v100, v100, v101
	v_cvt_pk_bf16_f32 v101, v102, v103
	v_cvt_pk_bf16_f32 v102, v104, v105
	v_cvt_pk_bf16_f32 v103, v106, v107
	v_cvt_pk_bf16_f32 v104, v108, v109
	v_cvt_pk_bf16_f32 v105, v110, v111
	v_cvt_pk_bf16_f32 v106, v112, v113
	v_cvt_pk_bf16_f32 v107, v114, v115
	s_add_u32 s50, s56, 0x400000
	s_addc_u32 s51, s57, 0
	global_store_dwordx4 v83, v[100:103], s[50:51]
	global_store_dwordx4 v83, v[104:107], s[50:51] offset:1024
	s_add_u32 s40, s97, s48
	s_addc_u32 s41, s3, 0
	s_add_u32 s40, s40, 0x1800000
	s_addc_u32 s41, s41, 0
	s_add_u32 s42, s54, 0x1b000
	s_addc_u32 s43, s55, 0
	s_add_u32 s44, s42, 0x1000
	s_addc_u32 s45, s43, 0
	global_load_dwordx4 v[100:103], v82, s[40:41]
	global_load_dwordx4 v[104:107], v82, s[40:41] offset:16
	global_load_dwordx4 v[108:111], v82, s[40:41] offset:2048
	global_load_dwordx4 v[112:115], v82, s[40:41] offset:2064
	global_load_dwordx4 v[116:119], v82, s[44:45]
	global_load_dwordx4 v[120:123], v82, s[44:45] offset:16
	global_load_dwordx4 v[124:127], v82, s[44:45] offset:2048
	global_load_dwordx4 v[128:131], v82, s[44:45] offset:2064
	global_load_dwordx4 v[132:135], v82, s[42:43]
	global_load_dwordx4 v[136:139], v82, s[42:43] offset:16
	global_load_dwordx4 v[140:143], v82, s[42:43] offset:2048
	global_load_dwordx4 v[144:147], v82, s[42:43] offset:2064
	s_waitcnt vmcnt(12)
	v_pk_mul_f32 v[54:55], v[0:1], v[0:1]
	v_pk_mul_f32 v[56:57], v[2:3], v[2:3]
	v_pk_fma_f32 v[54:55], v[4:5], v[4:5], v[54:55]
	v_pk_fma_f32 v[56:57], v[6:7], v[6:7], v[56:57]
	v_pk_fma_f32 v[54:55], v[8:9], v[8:9], v[54:55]
	v_pk_fma_f32 v[56:57], v[10:11], v[10:11], v[56:57]
	v_pk_fma_f32 v[54:55], v[12:13], v[12:13], v[54:55]
	v_pk_fma_f32 v[56:57], v[14:15], v[14:15], v[56:57]
	v_pk_add_f32 v[54:55], v[54:55], v[56:57]
	v_pk_fma_f32 v[16:17], v[84:85], v[16:17], v[84:85]
	v_add_f32_e32 v54, v54, v55
	v_pk_fma_f32 v[18:19], v[86:87], v[18:19], v[86:87]
	v_pk_fma_f32 v[20:21], v[88:89], v[20:21], v[88:89]
	v_add_f32_dpp v54, v54, v54 quad_perm:[1,0,3,2] row_mask:0xf bank_mask:0xf
	v_pk_fma_f32 v[22:23], v[90:91], v[22:23], v[90:91]
	v_pk_fma_f32 v[24:25], v[92:93], v[24:25], v[92:93]
	v_add_f32_dpp v54, v54, v54 quad_perm:[2,3,0,1] row_mask:0xf bank_mask:0xf
	v_pk_fma_f32 v[26:27], v[94:95], v[26:27], v[94:95]
	v_pk_fma_f32 v[28:29], v[96:97], v[28:29], v[96:97]
	v_add_f32_dpp v54, v54, v54 row_half_mirror row_mask:0xf bank_mask:0xf
	v_pk_fma_f32 v[30:31], v[98:99], v[30:31], v[98:99]
	s_nop 1
	v_add_f32_dpp v54, v54, v54 row_mirror row_mask:0xf bank_mask:0xf
	s_nop 0
	v_mov_b32_e32 v55, v54
	s_nop 1
	v_permlane16_swap_b32_e32 v54, v55
	s_nop 0
	v_add_f32_e32 v54, v54, v55
	s_nop 0
	v_mov_b32_e32 v55, v54
	s_nop 1
	v_permlane32_swap_b32_e32 v54, v55
	s_nop 0
	v_add_f32_e32 v54, v54, v55
	v_fmamk_f32 v54, v54, 0x3a800000, v227
	v_rsq_f32_e32 v54, v54
	s_nop 1
	v_pk_mul_f32 v[0:1], v[0:1], v[54:55] op_sel_hi:[1,0]
	v_pk_mul_f32 v[2:3], v[2:3], v[54:55] op_sel_hi:[1,0]
	v_pk_mul_f32 v[4:5], v[4:5], v[54:55] op_sel_hi:[1,0]
	v_pk_mul_f32 v[6:7], v[6:7], v[54:55] op_sel_hi:[1,0]
	v_pk_mul_f32 v[8:9], v[8:9], v[54:55] op_sel_hi:[1,0]
	v_pk_mul_f32 v[10:11], v[10:11], v[54:55] op_sel_hi:[1,0]
	v_pk_mul_f32 v[12:13], v[12:13], v[54:55] op_sel_hi:[1,0]
	v_pk_mul_f32 v[14:15], v[14:15], v[54:55] op_sel_hi:[1,0]
	v_pk_fma_f32 v[0:1], v[0:1], v[16:17], v[38:39]
	v_pk_fma_f32 v[2:3], v[2:3], v[18:19], v[40:41]
	v_pk_fma_f32 v[4:5], v[4:5], v[20:21], v[42:43]
	v_pk_fma_f32 v[6:7], v[6:7], v[22:23], v[44:45]
	v_pk_fma_f32 v[8:9], v[8:9], v[24:25], v[46:47]
	v_pk_fma_f32 v[10:11], v[10:11], v[26:27], v[48:49]
	v_pk_fma_f32 v[12:13], v[12:13], v[28:29], v[50:51]
	v_pk_fma_f32 v[14:15], v[14:15], v[30:31], v[52:53]
	v_cvt_pk_bf16_f32 v0, v0, v1
	v_cvt_pk_bf16_f32 v1, v2, v3
	v_cvt_pk_bf16_f32 v2, v4, v5
	v_cvt_pk_bf16_f32 v3, v6, v7
	v_cvt_pk_bf16_f32 v4, v8, v9
	v_cvt_pk_bf16_f32 v5, v10, v11
	v_cvt_pk_bf16_f32 v6, v12, v13
	v_cvt_pk_bf16_f32 v7, v14, v15
	s_add_u32 s50, s56, 0x800000
	s_addc_u32 s51, s57, 0
	global_store_dwordx4 v83, v[0:3], s[50:51]
	global_store_dwordx4 v83, v[4:7], s[50:51] offset:1024
	s_add_u32 s40, s97, s48
	s_addc_u32 s41, s3, 0
	s_add_u32 s40, s40, 0x2000000
	s_addc_u32 s41, s41, 0
	s_add_u32 s42, s54, 0x24000
	s_addc_u32 s43, s55, 0
	s_add_u32 s44, s42, 0x1000
	s_addc_u32 s45, s43, 0
	global_load_dwordx4 v[0:3], v82, s[40:41]
	global_load_dwordx4 v[4:7], v82, s[40:41] offset:16
	global_load_dwordx4 v[8:11], v82, s[40:41] offset:2048
	global_load_dwordx4 v[12:15], v82, s[40:41] offset:2064
	global_load_dwordx4 v[16:19], v82, s[44:45]
	global_load_dwordx4 v[20:23], v82, s[44:45] offset:16
	global_load_dwordx4 v[24:27], v82, s[44:45] offset:2048
	global_load_dwordx4 v[28:31], v82, s[44:45] offset:2064
	global_load_dwordx4 v[38:41], v82, s[42:43]
	global_load_dwordx4 v[42:45], v82, s[42:43] offset:16
	global_load_dwordx4 v[46:49], v82, s[42:43] offset:2048
	global_load_dwordx4 v[50:53], v82, s[42:43] offset:2064
	s_waitcnt vmcnt(12)
	v_pk_mul_f32 v[54:55], v[100:101], v[100:101]
	v_pk_mul_f32 v[56:57], v[102:103], v[102:103]
	v_pk_fma_f32 v[54:55], v[104:105], v[104:105], v[54:55]
	v_pk_fma_f32 v[56:57], v[106:107], v[106:107], v[56:57]
	v_pk_fma_f32 v[54:55], v[108:109], v[108:109], v[54:55]
	v_pk_fma_f32 v[56:57], v[110:111], v[110:111], v[56:57]
	v_pk_fma_f32 v[54:55], v[112:113], v[112:113], v[54:55]
	v_pk_fma_f32 v[56:57], v[114:115], v[114:115], v[56:57]
	v_pk_add_f32 v[54:55], v[54:55], v[56:57]
	v_pk_fma_f32 v[116:117], v[84:85], v[116:117], v[84:85]
	v_add_f32_e32 v54, v54, v55
	v_pk_fma_f32 v[118:119], v[86:87], v[118:119], v[86:87]
	v_pk_fma_f32 v[120:121], v[88:89], v[120:121], v[88:89]
	v_add_f32_dpp v54, v54, v54 quad_perm:[1,0,3,2] row_mask:0xf bank_mask:0xf
	v_pk_fma_f32 v[122:123], v[90:91], v[122:123], v[90:91]
	v_pk_fma_f32 v[124:125], v[92:93], v[124:125], v[92:93]
	v_add_f32_dpp v54, v54, v54 quad_perm:[2,3,0,1] row_mask:0xf bank_mask:0xf
	v_pk_fma_f32 v[126:127], v[94:95], v[126:127], v[94:95]
	v_pk_fma_f32 v[128:129], v[96:97], v[128:129], v[96:97]
	v_add_f32_dpp v54, v54, v54 row_half_mirror row_mask:0xf bank_mask:0xf
	v_pk_fma_f32 v[130:131], v[98:99], v[130:131], v[98:99]
	s_nop 1
	v_add_f32_dpp v54, v54, v54 row_mirror row_mask:0xf bank_mask:0xf
	s_nop 0
	v_mov_b32_e32 v55, v54
	s_nop 1
	v_permlane16_swap_b32_e32 v54, v55
	s_nop 0
	v_add_f32_e32 v54, v54, v55
	s_nop 0
	v_mov_b32_e32 v55, v54
	s_nop 1
	v_permlane32_swap_b32_e32 v54, v55
	s_nop 0
	v_add_f32_e32 v54, v54, v55
	v_fmamk_f32 v54, v54, 0x3a800000, v227
	v_rsq_f32_e32 v54, v54
	s_nop 1
	v_pk_mul_f32 v[100:101], v[100:101], v[54:55] op_sel_hi:[1,0]
	v_pk_mul_f32 v[102:103], v[102:103], v[54:55] op_sel_hi:[1,0]
	v_pk_mul_f32 v[104:105], v[104:105], v[54:55] op_sel_hi:[1,0]
	v_pk_mul_f32 v[106:107], v[106:107], v[54:55] op_sel_hi:[1,0]
	v_pk_mul_f32 v[108:109], v[108:109], v[54:55] op_sel_hi:[1,0]
	v_pk_mul_f32 v[110:111], v[110:111], v[54:55] op_sel_hi:[1,0]
	v_pk_mul_f32 v[112:113], v[112:113], v[54:55] op_sel_hi:[1,0]
	v_pk_mul_f32 v[114:115], v[114:115], v[54:55] op_sel_hi:[1,0]
	v_pk_fma_f32 v[100:101], v[100:101], v[116:117], v[132:133]
	v_pk_fma_f32 v[102:103], v[102:103], v[118:119], v[134:135]
	v_pk_fma_f32 v[104:105], v[104:105], v[120:121], v[136:137]
	v_pk_fma_f32 v[106:107], v[106:107], v[122:123], v[138:139]
	v_pk_fma_f32 v[108:109], v[108:109], v[124:125], v[140:141]
	v_pk_fma_f32 v[110:111], v[110:111], v[126:127], v[142:143]
	v_pk_fma_f32 v[112:113], v[112:113], v[128:129], v[144:145]
	v_pk_fma_f32 v[114:115], v[114:115], v[130:131], v[146:147]
	v_cvt_pk_bf16_f32 v100, v100, v101
	v_cvt_pk_bf16_f32 v101, v102, v103
	v_cvt_pk_bf16_f32 v102, v104, v105
	v_cvt_pk_bf16_f32 v103, v106, v107
	v_cvt_pk_bf16_f32 v104, v108, v109
	v_cvt_pk_bf16_f32 v105, v110, v111
	v_cvt_pk_bf16_f32 v106, v112, v113
	v_cvt_pk_bf16_f32 v107, v114, v115
	s_add_u32 s50, s56, 0xc00000
	s_addc_u32 s51, s57, 0
	global_store_dwordx4 v83, v[100:103], s[50:51]
	global_store_dwordx4 v83, v[104:107], s[50:51] offset:1024
	s_add_u32 s40, s97, s48
	s_addc_u32 s41, s3, 0
	s_add_u32 s40, s40, 0x2800000
	s_addc_u32 s41, s41, 0
	s_add_u32 s42, s54, 0x2d000
	s_addc_u32 s43, s55, 0
	s_add_u32 s44, s42, 0x1000
	s_addc_u32 s45, s43, 0
	global_load_dwordx4 v[100:103], v82, s[40:41]
	global_load_dwordx4 v[104:107], v82, s[40:41] offset:16
	global_load_dwordx4 v[108:111], v82, s[40:41] offset:2048
	global_load_dwordx4 v[112:115], v82, s[40:41] offset:2064
	global_load_dwordx4 v[116:119], v82, s[44:45]
	global_load_dwordx4 v[120:123], v82, s[44:45] offset:16
	global_load_dwordx4 v[124:127], v82, s[44:45] offset:2048
	global_load_dwordx4 v[128:131], v82, s[44:45] offset:2064
	global_load_dwordx4 v[132:135], v82, s[42:43]
	global_load_dwordx4 v[136:139], v82, s[42:43] offset:16
	global_load_dwordx4 v[140:143], v82, s[42:43] offset:2048
	global_load_dwordx4 v[144:147], v82, s[42:43] offset:2064
	s_waitcnt vmcnt(12)
	v_pk_mul_f32 v[54:55], v[0:1], v[0:1]
	v_pk_mul_f32 v[56:57], v[2:3], v[2:3]
	v_pk_fma_f32 v[54:55], v[4:5], v[4:5], v[54:55]
	v_pk_fma_f32 v[56:57], v[6:7], v[6:7], v[56:57]
	v_pk_fma_f32 v[54:55], v[8:9], v[8:9], v[54:55]
	v_pk_fma_f32 v[56:57], v[10:11], v[10:11], v[56:57]
	v_pk_fma_f32 v[54:55], v[12:13], v[12:13], v[54:55]
	v_pk_fma_f32 v[56:57], v[14:15], v[14:15], v[56:57]
	v_pk_add_f32 v[54:55], v[54:55], v[56:57]
	v_pk_fma_f32 v[16:17], v[84:85], v[16:17], v[84:85]
	v_add_f32_e32 v54, v54, v55
	v_pk_fma_f32 v[18:19], v[86:87], v[18:19], v[86:87]
	v_pk_fma_f32 v[20:21], v[88:89], v[20:21], v[88:89]
	v_add_f32_dpp v54, v54, v54 quad_perm:[1,0,3,2] row_mask:0xf bank_mask:0xf
	v_pk_fma_f32 v[22:23], v[90:91], v[22:23], v[90:91]
	v_pk_fma_f32 v[24:25], v[92:93], v[24:25], v[92:93]
	v_add_f32_dpp v54, v54, v54 quad_perm:[2,3,0,1] row_mask:0xf bank_mask:0xf
	v_pk_fma_f32 v[26:27], v[94:95], v[26:27], v[94:95]
	v_pk_fma_f32 v[28:29], v[96:97], v[28:29], v[96:97]
	v_add_f32_dpp v54, v54, v54 row_half_mirror row_mask:0xf bank_mask:0xf
	v_pk_fma_f32 v[30:31], v[98:99], v[30:31], v[98:99]
	s_nop 1
	v_add_f32_dpp v54, v54, v54 row_mirror row_mask:0xf bank_mask:0xf
	s_nop 0
	v_mov_b32_e32 v55, v54
	s_nop 1
	v_permlane16_swap_b32_e32 v54, v55
	s_nop 0
	v_add_f32_e32 v54, v54, v55
	s_nop 0
	v_mov_b32_e32 v55, v54
	s_nop 1
	v_permlane32_swap_b32_e32 v54, v55
	s_nop 0
	v_add_f32_e32 v54, v54, v55
	v_fmamk_f32 v54, v54, 0x3a800000, v227
	v_rsq_f32_e32 v54, v54
	s_nop 1
	v_pk_mul_f32 v[0:1], v[0:1], v[54:55] op_sel_hi:[1,0]
	v_pk_mul_f32 v[2:3], v[2:3], v[54:55] op_sel_hi:[1,0]
	v_pk_mul_f32 v[4:5], v[4:5], v[54:55] op_sel_hi:[1,0]
	v_pk_mul_f32 v[6:7], v[6:7], v[54:55] op_sel_hi:[1,0]
	v_pk_mul_f32 v[8:9], v[8:9], v[54:55] op_sel_hi:[1,0]
	v_pk_mul_f32 v[10:11], v[10:11], v[54:55] op_sel_hi:[1,0]
	v_pk_mul_f32 v[12:13], v[12:13], v[54:55] op_sel_hi:[1,0]
	v_pk_mul_f32 v[14:15], v[14:15], v[54:55] op_sel_hi:[1,0]
	v_pk_fma_f32 v[0:1], v[0:1], v[16:17], v[38:39]
	v_pk_fma_f32 v[2:3], v[2:3], v[18:19], v[40:41]
	v_pk_fma_f32 v[4:5], v[4:5], v[20:21], v[42:43]
	v_pk_fma_f32 v[6:7], v[6:7], v[22:23], v[44:45]
	v_pk_fma_f32 v[8:9], v[8:9], v[24:25], v[46:47]
	v_pk_fma_f32 v[10:11], v[10:11], v[26:27], v[48:49]
	v_pk_fma_f32 v[12:13], v[12:13], v[28:29], v[50:51]
	v_pk_fma_f32 v[14:15], v[14:15], v[30:31], v[52:53]
	v_cvt_pk_bf16_f32 v0, v0, v1
	v_cvt_pk_bf16_f32 v1, v2, v3
	v_cvt_pk_bf16_f32 v2, v4, v5
	v_cvt_pk_bf16_f32 v3, v6, v7
	v_cvt_pk_bf16_f32 v4, v8, v9
	v_cvt_pk_bf16_f32 v5, v10, v11
	v_cvt_pk_bf16_f32 v6, v12, v13
	v_cvt_pk_bf16_f32 v7, v14, v15
	s_add_u32 s50, s56, 0x1000000
	s_addc_u32 s51, s57, 0
	global_store_dwordx4 v83, v[0:3], s[50:51]
	global_store_dwordx4 v83, v[4:7], s[50:51] offset:1024
	s_add_u32 s40, s97, s48
	s_addc_u32 s41, s3, 0
	s_add_u32 s40, s40, 0x3000000
	s_addc_u32 s41, s41, 0
	s_add_u32 s42, s54, 0x36000
	s_addc_u32 s43, s55, 0
	s_add_u32 s44, s42, 0x1000
	s_addc_u32 s45, s43, 0
	global_load_dwordx4 v[0:3], v82, s[40:41]
	global_load_dwordx4 v[4:7], v82, s[40:41] offset:16
	global_load_dwordx4 v[8:11], v82, s[40:41] offset:2048
	global_load_dwordx4 v[12:15], v82, s[40:41] offset:2064
	global_load_dwordx4 v[16:19], v82, s[44:45]
	global_load_dwordx4 v[20:23], v82, s[44:45] offset:16
	global_load_dwordx4 v[24:27], v82, s[44:45] offset:2048
	global_load_dwordx4 v[28:31], v82, s[44:45] offset:2064
	global_load_dwordx4 v[38:41], v82, s[42:43]
	global_load_dwordx4 v[42:45], v82, s[42:43] offset:16
	global_load_dwordx4 v[46:49], v82, s[42:43] offset:2048
	global_load_dwordx4 v[50:53], v82, s[42:43] offset:2064
	s_waitcnt vmcnt(12)
	v_pk_mul_f32 v[54:55], v[100:101], v[100:101]
	v_pk_mul_f32 v[56:57], v[102:103], v[102:103]
	v_pk_fma_f32 v[54:55], v[104:105], v[104:105], v[54:55]
	v_pk_fma_f32 v[56:57], v[106:107], v[106:107], v[56:57]
	v_pk_fma_f32 v[54:55], v[108:109], v[108:109], v[54:55]
	v_pk_fma_f32 v[56:57], v[110:111], v[110:111], v[56:57]
	v_pk_fma_f32 v[54:55], v[112:113], v[112:113], v[54:55]
	v_pk_fma_f32 v[56:57], v[114:115], v[114:115], v[56:57]
	v_pk_add_f32 v[54:55], v[54:55], v[56:57]
	v_pk_fma_f32 v[116:117], v[84:85], v[116:117], v[84:85]
	v_add_f32_e32 v54, v54, v55
	v_pk_fma_f32 v[118:119], v[86:87], v[118:119], v[86:87]
	v_pk_fma_f32 v[120:121], v[88:89], v[120:121], v[88:89]
	v_add_f32_dpp v54, v54, v54 quad_perm:[1,0,3,2] row_mask:0xf bank_mask:0xf
	v_pk_fma_f32 v[122:123], v[90:91], v[122:123], v[90:91]
	v_pk_fma_f32 v[124:125], v[92:93], v[124:125], v[92:93]
	v_add_f32_dpp v54, v54, v54 quad_perm:[2,3,0,1] row_mask:0xf bank_mask:0xf
	v_pk_fma_f32 v[126:127], v[94:95], v[126:127], v[94:95]
	v_pk_fma_f32 v[128:129], v[96:97], v[128:129], v[96:97]
	v_add_f32_dpp v54, v54, v54 row_half_mirror row_mask:0xf bank_mask:0xf
	v_pk_fma_f32 v[130:131], v[98:99], v[130:131], v[98:99]
	s_nop 1
	v_add_f32_dpp v54, v54, v54 row_mirror row_mask:0xf bank_mask:0xf
	s_nop 0
	v_mov_b32_e32 v55, v54
	s_nop 1
	v_permlane16_swap_b32_e32 v54, v55
	s_nop 0
	v_add_f32_e32 v54, v54, v55
	s_nop 0
	v_mov_b32_e32 v55, v54
	s_nop 1
	v_permlane32_swap_b32_e32 v54, v55
	s_nop 0
	v_add_f32_e32 v54, v54, v55
	v_fmamk_f32 v54, v54, 0x3a800000, v227
	v_rsq_f32_e32 v54, v54
	s_nop 1
	v_pk_mul_f32 v[100:101], v[100:101], v[54:55] op_sel_hi:[1,0]
	v_pk_mul_f32 v[102:103], v[102:103], v[54:55] op_sel_hi:[1,0]
	v_pk_mul_f32 v[104:105], v[104:105], v[54:55] op_sel_hi:[1,0]
	v_pk_mul_f32 v[106:107], v[106:107], v[54:55] op_sel_hi:[1,0]
	v_pk_mul_f32 v[108:109], v[108:109], v[54:55] op_sel_hi:[1,0]
	v_pk_mul_f32 v[110:111], v[110:111], v[54:55] op_sel_hi:[1,0]
	v_pk_mul_f32 v[112:113], v[112:113], v[54:55] op_sel_hi:[1,0]
	v_pk_mul_f32 v[114:115], v[114:115], v[54:55] op_sel_hi:[1,0]
	v_pk_fma_f32 v[100:101], v[100:101], v[116:117], v[132:133]
	v_pk_fma_f32 v[102:103], v[102:103], v[118:119], v[134:135]
	v_pk_fma_f32 v[104:105], v[104:105], v[120:121], v[136:137]
	v_pk_fma_f32 v[106:107], v[106:107], v[122:123], v[138:139]
	v_pk_fma_f32 v[108:109], v[108:109], v[124:125], v[140:141]
	v_pk_fma_f32 v[110:111], v[110:111], v[126:127], v[142:143]
	v_pk_fma_f32 v[112:113], v[112:113], v[128:129], v[144:145]
	v_pk_fma_f32 v[114:115], v[114:115], v[130:131], v[146:147]
	v_cvt_pk_bf16_f32 v100, v100, v101
	v_cvt_pk_bf16_f32 v101, v102, v103
	v_cvt_pk_bf16_f32 v102, v104, v105
	v_cvt_pk_bf16_f32 v103, v106, v107
	v_cvt_pk_bf16_f32 v104, v108, v109
	v_cvt_pk_bf16_f32 v105, v110, v111
	v_cvt_pk_bf16_f32 v106, v112, v113
	v_cvt_pk_bf16_f32 v107, v114, v115
	s_add_u32 s50, s56, 0x1400000
	s_addc_u32 s51, s57, 0
	global_store_dwordx4 v83, v[100:103], s[50:51]
	global_store_dwordx4 v83, v[104:107], s[50:51] offset:1024
	s_add_u32 s40, s97, s48
	s_addc_u32 s41, s3, 0
	s_add_u32 s40, s40, 0x3800000
	s_addc_u32 s41, s41, 0
	s_add_u32 s42, s54, 0x3f000
	s_addc_u32 s43, s55, 0
	s_add_u32 s44, s42, 0x1000
	s_addc_u32 s45, s43, 0
	global_load_dwordx4 v[100:103], v82, s[40:41]
	global_load_dwordx4 v[104:107], v82, s[40:41] offset:16
	global_load_dwordx4 v[108:111], v82, s[40:41] offset:2048
	global_load_dwordx4 v[112:115], v82, s[40:41] offset:2064
	global_load_dwordx4 v[116:119], v82, s[44:45]
	global_load_dwordx4 v[120:123], v82, s[44:45] offset:16
	global_load_dwordx4 v[124:127], v82, s[44:45] offset:2048
	global_load_dwordx4 v[128:131], v82, s[44:45] offset:2064
	global_load_dwordx4 v[132:135], v82, s[42:43]
	global_load_dwordx4 v[136:139], v82, s[42:43] offset:16
	global_load_dwordx4 v[140:143], v82, s[42:43] offset:2048
	global_load_dwordx4 v[144:147], v82, s[42:43] offset:2064
	s_waitcnt vmcnt(12)
	v_pk_mul_f32 v[54:55], v[0:1], v[0:1]
	v_pk_mul_f32 v[56:57], v[2:3], v[2:3]
	v_pk_fma_f32 v[54:55], v[4:5], v[4:5], v[54:55]
	v_pk_fma_f32 v[56:57], v[6:7], v[6:7], v[56:57]
	v_pk_fma_f32 v[54:55], v[8:9], v[8:9], v[54:55]
	v_pk_fma_f32 v[56:57], v[10:11], v[10:11], v[56:57]
	v_pk_fma_f32 v[54:55], v[12:13], v[12:13], v[54:55]
	v_pk_fma_f32 v[56:57], v[14:15], v[14:15], v[56:57]
	v_pk_add_f32 v[54:55], v[54:55], v[56:57]
	v_pk_fma_f32 v[16:17], v[84:85], v[16:17], v[84:85]
	v_add_f32_e32 v54, v54, v55
	v_pk_fma_f32 v[18:19], v[86:87], v[18:19], v[86:87]
	v_pk_fma_f32 v[20:21], v[88:89], v[20:21], v[88:89]
	v_add_f32_dpp v54, v54, v54 quad_perm:[1,0,3,2] row_mask:0xf bank_mask:0xf
	v_pk_fma_f32 v[22:23], v[90:91], v[22:23], v[90:91]
	v_pk_fma_f32 v[24:25], v[92:93], v[24:25], v[92:93]
	v_add_f32_dpp v54, v54, v54 quad_perm:[2,3,0,1] row_mask:0xf bank_mask:0xf
	v_pk_fma_f32 v[26:27], v[94:95], v[26:27], v[94:95]
	v_pk_fma_f32 v[28:29], v[96:97], v[28:29], v[96:97]
	v_add_f32_dpp v54, v54, v54 row_half_mirror row_mask:0xf bank_mask:0xf
	v_pk_fma_f32 v[30:31], v[98:99], v[30:31], v[98:99]
	s_nop 1
	v_add_f32_dpp v54, v54, v54 row_mirror row_mask:0xf bank_mask:0xf
	s_nop 0
	v_mov_b32_e32 v55, v54
	s_nop 1
	v_permlane16_swap_b32_e32 v54, v55
	s_nop 0
	v_add_f32_e32 v54, v54, v55
	s_nop 0
	v_mov_b32_e32 v55, v54
	s_nop 1
	v_permlane32_swap_b32_e32 v54, v55
	s_nop 0
	v_add_f32_e32 v54, v54, v55
	v_fmamk_f32 v54, v54, 0x3a800000, v227
	v_rsq_f32_e32 v54, v54
	s_nop 1
	v_pk_mul_f32 v[0:1], v[0:1], v[54:55] op_sel_hi:[1,0]
	v_pk_mul_f32 v[2:3], v[2:3], v[54:55] op_sel_hi:[1,0]
	v_pk_mul_f32 v[4:5], v[4:5], v[54:55] op_sel_hi:[1,0]
	v_pk_mul_f32 v[6:7], v[6:7], v[54:55] op_sel_hi:[1,0]
	v_pk_mul_f32 v[8:9], v[8:9], v[54:55] op_sel_hi:[1,0]
	v_pk_mul_f32 v[10:11], v[10:11], v[54:55] op_sel_hi:[1,0]
	v_pk_mul_f32 v[12:13], v[12:13], v[54:55] op_sel_hi:[1,0]
	v_pk_mul_f32 v[14:15], v[14:15], v[54:55] op_sel_hi:[1,0]
	v_pk_fma_f32 v[0:1], v[0:1], v[16:17], v[38:39]
	v_pk_fma_f32 v[2:3], v[2:3], v[18:19], v[40:41]
	v_pk_fma_f32 v[4:5], v[4:5], v[20:21], v[42:43]
	v_pk_fma_f32 v[6:7], v[6:7], v[22:23], v[44:45]
	v_pk_fma_f32 v[8:9], v[8:9], v[24:25], v[46:47]
	v_pk_fma_f32 v[10:11], v[10:11], v[26:27], v[48:49]
	v_pk_fma_f32 v[12:13], v[12:13], v[28:29], v[50:51]
	v_pk_fma_f32 v[14:15], v[14:15], v[30:31], v[52:53]
	v_cvt_pk_bf16_f32 v0, v0, v1
	v_cvt_pk_bf16_f32 v1, v2, v3
	v_cvt_pk_bf16_f32 v2, v4, v5
	v_cvt_pk_bf16_f32 v3, v6, v7
	v_cvt_pk_bf16_f32 v4, v8, v9
	v_cvt_pk_bf16_f32 v5, v10, v11
	v_cvt_pk_bf16_f32 v6, v12, v13
	v_cvt_pk_bf16_f32 v7, v14, v15
	s_add_u32 s50, s56, 0x1800000
	s_addc_u32 s51, s57, 0
	global_store_dwordx4 v83, v[0:3], s[50:51]
	global_store_dwordx4 v83, v[4:7], s[50:51] offset:1024
	s_add_u32 s40, s28, s48
	s_addc_u32 s41, s2, 0
	s_add_u32 s42, s54, 0x48000
	s_addc_u32 s43, s55, 0
	s_add_u32 s44, s42, 0x1000
	s_addc_u32 s45, s43, 0
	global_load_dwordx4 v[0:3], v82, s[40:41]
	global_load_dwordx4 v[4:7], v82, s[40:41] offset:16
	global_load_dwordx4 v[8:11], v82, s[40:41] offset:2048
	global_load_dwordx4 v[12:15], v82, s[40:41] offset:2064
	global_load_dwordx4 v[16:19], v82, s[44:45]
	global_load_dwordx4 v[20:23], v82, s[44:45] offset:16
	global_load_dwordx4 v[24:27], v82, s[44:45] offset:2048
	global_load_dwordx4 v[28:31], v82, s[44:45] offset:2064
	global_load_dwordx4 v[38:41], v82, s[42:43]
	global_load_dwordx4 v[42:45], v82, s[42:43] offset:16
	global_load_dwordx4 v[46:49], v82, s[42:43] offset:2048
	global_load_dwordx4 v[50:53], v82, s[42:43] offset:2064
	s_waitcnt vmcnt(12)
	v_pk_mul_f32 v[54:55], v[100:101], v[100:101]
	v_pk_mul_f32 v[56:57], v[102:103], v[102:103]
	v_pk_fma_f32 v[54:55], v[104:105], v[104:105], v[54:55]
	v_pk_fma_f32 v[56:57], v[106:107], v[106:107], v[56:57]
	v_pk_fma_f32 v[54:55], v[108:109], v[108:109], v[54:55]
	v_pk_fma_f32 v[56:57], v[110:111], v[110:111], v[56:57]
	v_pk_fma_f32 v[54:55], v[112:113], v[112:113], v[54:55]
	v_pk_fma_f32 v[56:57], v[114:115], v[114:115], v[56:57]
	v_pk_add_f32 v[54:55], v[54:55], v[56:57]
	v_pk_fma_f32 v[116:117], v[84:85], v[116:117], v[84:85]
	v_add_f32_e32 v54, v54, v55
	v_pk_fma_f32 v[118:119], v[86:87], v[118:119], v[86:87]
	v_pk_fma_f32 v[120:121], v[88:89], v[120:121], v[88:89]
	v_add_f32_dpp v54, v54, v54 quad_perm:[1,0,3,2] row_mask:0xf bank_mask:0xf
	v_pk_fma_f32 v[122:123], v[90:91], v[122:123], v[90:91]
	v_pk_fma_f32 v[124:125], v[92:93], v[124:125], v[92:93]
	v_add_f32_dpp v54, v54, v54 quad_perm:[2,3,0,1] row_mask:0xf bank_mask:0xf
	v_pk_fma_f32 v[126:127], v[94:95], v[126:127], v[94:95]
	v_pk_fma_f32 v[128:129], v[96:97], v[128:129], v[96:97]
	v_add_f32_dpp v54, v54, v54 row_half_mirror row_mask:0xf bank_mask:0xf
	v_pk_fma_f32 v[130:131], v[98:99], v[130:131], v[98:99]
	s_nop 1
	v_add_f32_dpp v54, v54, v54 row_mirror row_mask:0xf bank_mask:0xf
	s_nop 0
	v_mov_b32_e32 v55, v54
	s_nop 1
	v_permlane16_swap_b32_e32 v54, v55
	s_nop 0
	v_add_f32_e32 v54, v54, v55
	s_nop 0
	v_mov_b32_e32 v55, v54
	s_nop 1
	v_permlane32_swap_b32_e32 v54, v55
	s_nop 0
	v_add_f32_e32 v54, v54, v55
	v_fmamk_f32 v54, v54, 0x3a800000, v227
	v_rsq_f32_e32 v54, v54
	s_nop 1
	v_pk_mul_f32 v[100:101], v[100:101], v[54:55] op_sel_hi:[1,0]
	v_pk_mul_f32 v[102:103], v[102:103], v[54:55] op_sel_hi:[1,0]
	v_pk_mul_f32 v[104:105], v[104:105], v[54:55] op_sel_hi:[1,0]
	v_pk_mul_f32 v[106:107], v[106:107], v[54:55] op_sel_hi:[1,0]
	v_pk_mul_f32 v[108:109], v[108:109], v[54:55] op_sel_hi:[1,0]
	v_pk_mul_f32 v[110:111], v[110:111], v[54:55] op_sel_hi:[1,0]
	v_pk_mul_f32 v[112:113], v[112:113], v[54:55] op_sel_hi:[1,0]
	v_pk_mul_f32 v[114:115], v[114:115], v[54:55] op_sel_hi:[1,0]
	v_pk_fma_f32 v[100:101], v[100:101], v[116:117], v[132:133]
	v_pk_fma_f32 v[102:103], v[102:103], v[118:119], v[134:135]
	v_pk_fma_f32 v[104:105], v[104:105], v[120:121], v[136:137]
	v_pk_fma_f32 v[106:107], v[106:107], v[122:123], v[138:139]
	v_pk_fma_f32 v[108:109], v[108:109], v[124:125], v[140:141]
	v_pk_fma_f32 v[110:111], v[110:111], v[126:127], v[142:143]
	v_pk_fma_f32 v[112:113], v[112:113], v[128:129], v[144:145]
	v_pk_fma_f32 v[114:115], v[114:115], v[130:131], v[146:147]
	v_cvt_pk_bf16_f32 v100, v100, v101
	v_cvt_pk_bf16_f32 v101, v102, v103
	v_cvt_pk_bf16_f32 v102, v104, v105
	v_cvt_pk_bf16_f32 v103, v106, v107
	v_cvt_pk_bf16_f32 v104, v108, v109
	v_cvt_pk_bf16_f32 v105, v110, v111
	v_cvt_pk_bf16_f32 v106, v112, v113
	v_cvt_pk_bf16_f32 v107, v114, v115
	s_add_u32 s50, s56, 0x1c00000
	s_addc_u32 s51, s57, 0
	global_store_dwordx4 v83, v[100:103], s[50:51]
	global_store_dwordx4 v83, v[104:107], s[50:51] offset:1024
	s_waitcnt vmcnt(0)
	v_pk_mul_f32 v[54:55], v[0:1], v[0:1]
	v_pk_mul_f32 v[56:57], v[2:3], v[2:3]
	v_pk_fma_f32 v[54:55], v[4:5], v[4:5], v[54:55]
	v_pk_fma_f32 v[56:57], v[6:7], v[6:7], v[56:57]
	v_pk_fma_f32 v[54:55], v[8:9], v[8:9], v[54:55]
	v_pk_fma_f32 v[56:57], v[10:11], v[10:11], v[56:57]
	v_pk_fma_f32 v[54:55], v[12:13], v[12:13], v[54:55]
	v_pk_fma_f32 v[56:57], v[14:15], v[14:15], v[56:57]
	v_pk_add_f32 v[54:55], v[54:55], v[56:57]
	v_pk_fma_f32 v[16:17], v[84:85], v[16:17], v[84:85]
	v_add_f32_e32 v54, v54, v55
	v_pk_fma_f32 v[18:19], v[86:87], v[18:19], v[86:87]
	v_pk_fma_f32 v[20:21], v[88:89], v[20:21], v[88:89]
	v_add_f32_dpp v54, v54, v54 quad_perm:[1,0,3,2] row_mask:0xf bank_mask:0xf
	v_pk_fma_f32 v[22:23], v[90:91], v[22:23], v[90:91]
	v_pk_fma_f32 v[24:25], v[92:93], v[24:25], v[92:93]
	v_add_f32_dpp v54, v54, v54 quad_perm:[2,3,0,1] row_mask:0xf bank_mask:0xf
	v_pk_fma_f32 v[26:27], v[94:95], v[26:27], v[94:95]
	v_pk_fma_f32 v[28:29], v[96:97], v[28:29], v[96:97]
	v_add_f32_dpp v54, v54, v54 row_half_mirror row_mask:0xf bank_mask:0xf
	v_pk_fma_f32 v[30:31], v[98:99], v[30:31], v[98:99]
	s_nop 1
	v_add_f32_dpp v54, v54, v54 row_mirror row_mask:0xf bank_mask:0xf
	s_nop 0
	v_mov_b32_e32 v55, v54
	s_nop 1
	v_permlane16_swap_b32_e32 v54, v55
	s_nop 0
	v_add_f32_e32 v54, v54, v55
	s_nop 0
	v_mov_b32_e32 v55, v54
	s_nop 1
	v_permlane32_swap_b32_e32 v54, v55
	s_nop 0
	v_add_f32_e32 v54, v54, v55
	v_fmamk_f32 v54, v54, 0x3a800000, v227
	v_rsq_f32_e32 v54, v54
	s_nop 1
	v_pk_mul_f32 v[0:1], v[0:1], v[54:55] op_sel_hi:[1,0]
	v_pk_mul_f32 v[2:3], v[2:3], v[54:55] op_sel_hi:[1,0]
	v_pk_mul_f32 v[4:5], v[4:5], v[54:55] op_sel_hi:[1,0]
	v_pk_mul_f32 v[6:7], v[6:7], v[54:55] op_sel_hi:[1,0]
	v_pk_mul_f32 v[8:9], v[8:9], v[54:55] op_sel_hi:[1,0]
	v_pk_mul_f32 v[10:11], v[10:11], v[54:55] op_sel_hi:[1,0]
	v_pk_mul_f32 v[12:13], v[12:13], v[54:55] op_sel_hi:[1,0]
	v_pk_mul_f32 v[14:15], v[14:15], v[54:55] op_sel_hi:[1,0]
	v_pk_fma_f32 v[0:1], v[0:1], v[16:17], v[38:39]
	v_pk_fma_f32 v[2:3], v[2:3], v[18:19], v[40:41]
	v_pk_fma_f32 v[4:5], v[4:5], v[20:21], v[42:43]
	v_pk_fma_f32 v[6:7], v[6:7], v[22:23], v[44:45]
	v_pk_fma_f32 v[8:9], v[8:9], v[24:25], v[46:47]
	v_pk_fma_f32 v[10:11], v[10:11], v[26:27], v[48:49]
	v_pk_fma_f32 v[12:13], v[12:13], v[28:29], v[50:51]
	v_pk_fma_f32 v[14:15], v[14:15], v[30:31], v[52:53]
	v_cvt_pk_bf16_f32 v0, v0, v1
	v_cvt_pk_bf16_f32 v1, v2, v3
	v_cvt_pk_bf16_f32 v2, v4, v5
	v_cvt_pk_bf16_f32 v3, v6, v7
	v_cvt_pk_bf16_f32 v4, v8, v9
	v_cvt_pk_bf16_f32 v5, v10, v11
	v_cvt_pk_bf16_f32 v6, v12, v13
	v_cvt_pk_bf16_f32 v7, v14, v15
	s_add_u32 s50, s56, 0x2000000
	s_addc_u32 s51, s57, 0
	global_store_dwordx4 v83, v[0:3], s[50:51]
	global_store_dwordx4 v83, v[4:7], s[50:51] offset:1024

.LBB0_584:
	s_or_b64 exec, exec, s[44:45]
	s_waitcnt lgkmcnt(0)
	s_barrier
	v_lshl_add_u64 v[212:213], v[184:185], 2, s[26:27]
	global_load_dwordx4 v[46:49], v[212:213], off
	global_load_dwordx4 v[142:145], v[212:213], off offset:64
	global_load_dwordx4 v[154:157], v[212:213], off offset:512
	global_load_dwordx4 v[158:161], v[212:213], off offset:576
	s_mov_b64 s[26:27], 0xffffffff
	v_mov_b64_e32 v[138:139], s[26:27]
	s_add_u32 s28, s41, s34
	s_mul_i32 s27, s2, 0xc00
	s_mov_b32 s26, s1
	s_addc_u32 s31, s39, s35
	s_ashr_i64 s[26:27], s[26:27], 30
	s_add_u32 s26, s28, s26
	v_mov_b32_e32 v178, v33
	v_cmp_gt_u64_e64 s[44:45], s[60:61], v[138:139]
	s_addc_u32 s27, s31, s27
	v_cmp_lt_u64_e64 s[46:47], s[60:61], v[178:179]
	v_mov_b32_e32 v138, 0
	v_readlane_b32 s28, v252, 2
	s_nop 1
	v_cndmask_b32_e64 v32, 0, 1, s[46:47]
	s_nop 0
	v_cmp_ne_u32_e64 s[42:43], 1, v32
	s_nop 3
	s_and_b64 vcc, exec, s[44:45]
	s_cbranch_vccnz .Lmy_gs1_mode1
	v_lshl_add_u64 v[214:215], v[184:185], 2, s[26:27]
	s_add_u32 s98, s26, 0x1000
	s_addc_u32 s99, s27, 0
	v_lshl_add_u64 v[216:217], v[184:185], 2, s[98:99]
	global_load_dwordx4 v[146:149], v[214:215], off
	global_load_dwordx4 v[138:141], v[214:215], off offset:64
	global_load_dwordx4 v[162:165], v[214:215], off offset:512
	global_load_dwordx4 v[150:153], v[214:215], off offset:576
	global_load_dwordx4 v[166:169], v[216:217], off
	global_load_dwordx4 v[218:221], v[216:217], off offset:64
	global_load_dwordx4 v[222:225], v[216:217], off offset:512
	s_nop 0
	global_load_dwordx4 v[212:215], v[216:217], off offset:576
	s_waitcnt vmcnt(0)
	v_pk_add_f32 v[166:167], v[166:167], 1.0 op_sel_hi:[1,0]
	v_pk_add_f32 v[168:169], v[168:169], 1.0 op_sel_hi:[1,0]
	v_pk_add_f32 v[218:219], v[218:219], 1.0 op_sel_hi:[1,0]
	v_pk_add_f32 v[220:221], v[220:221], 1.0 op_sel_hi:[1,0]
	v_pk_add_f32 v[222:223], v[222:223], 1.0 op_sel_hi:[1,0]
	v_pk_add_f32 v[224:225], v[224:225], 1.0 op_sel_hi:[1,0]
	v_pk_add_f32 v[212:213], v[212:213], 1.0 op_sel_hi:[1,0]
	v_pk_add_f32 v[214:215], v[214:215], 1.0 op_sel_hi:[1,0]
	v_pk_mul_f32 v[46:47], v[46:47], v[166:167]
	v_pk_mul_f32 v[48:49], v[48:49], v[168:169]
	v_pk_mul_f32 v[142:143], v[142:143], v[218:219]
	v_pk_mul_f32 v[144:145], v[144:145], v[220:221]
	v_pk_mul_f32 v[154:155], v[154:155], v[222:223]
	v_pk_mul_f32 v[156:157], v[156:157], v[224:225]
	v_pk_mul_f32 v[158:159], v[158:159], v[212:213]
	v_pk_mul_f32 v[160:161], v[160:161], v[214:215]
	s_branch .LBB0_596
.Lmy_gs1_mode1:
	v_mov_b32_e32 v146, 0
	v_mov_b32_e32 v147, 0
	v_mov_b32_e32 v148, 0
	v_mov_b32_e32 v149, 0
	v_mov_b32_e32 v139, 0
	v_mov_b32_e32 v140, 0
	v_mov_b32_e32 v141, 0
	v_mov_b32_e32 v162, 0
	v_mov_b32_e32 v163, 0
	v_mov_b32_e32 v164, 0
	v_mov_b32_e32 v165, 0
	v_mov_b32_e32 v150, 0
	v_mov_b32_e32 v151, 0
	v_mov_b32_e32 v152, 0
	v_mov_b32_e32 v153, 0
	s_waitcnt vmcnt(0)

.LBB0_912:
	s_or_b64 exec, exec, s[44:45]
	s_waitcnt lgkmcnt(0)
	s_barrier
	v_lshl_add_u64 v[212:213], v[184:185], 2, s[26:27]
	global_load_dwordx4 v[58:61], v[212:213], off
	global_load_dwordx4 v[142:145], v[212:213], off offset:64
	global_load_dwordx4 v[154:157], v[212:213], off offset:512
	global_load_dwordx4 v[158:161], v[212:213], off offset:576
	s_mov_b64 s[26:27], 0xffffffff
	v_mov_b64_e32 v[138:139], s[26:27]
	s_add_u32 s0, s39, s34
	s_mul_i32 s27, s30, 0xc00
	s_mov_b32 s26, s1
	s_addc_u32 s28, s28, s35
	s_ashr_i64 s[26:27], s[26:27], 30
	s_add_u32 s26, s0, s26
	v_mov_b32_e32 v178, v33
	v_cmp_gt_u64_e64 s[44:45], s[48:49], v[138:139]
	s_addc_u32 s27, s28, s27
	v_cmp_lt_u64_e64 s[46:47], s[48:49], v[178:179]
	v_mov_b32_e32 v138, 0
	s_nop 2
	v_cndmask_b32_e64 v32, 0, 1, s[46:47]
	s_nop 0
	v_cmp_ne_u32_e64 s[42:43], 1, v32
	s_nop 3
	s_and_b64 vcc, exec, s[44:45]
	s_cbranch_vccnz .Lmy_gs2_mode1
	v_lshl_add_u64 v[214:215], v[184:185], 2, s[26:27]
	s_add_u32 s98, s26, 0x1000
	s_addc_u32 s99, s27, 0
	v_lshl_add_u64 v[216:217], v[184:185], 2, s[98:99]
	global_load_dwordx4 v[146:149], v[214:215], off
	global_load_dwordx4 v[138:141], v[214:215], off offset:64
	global_load_dwordx4 v[162:165], v[214:215], off offset:512
	global_load_dwordx4 v[150:153], v[214:215], off offset:576
	global_load_dwordx4 v[166:169], v[216:217], off
	global_load_dwordx4 v[218:221], v[216:217], off offset:64
	global_load_dwordx4 v[222:225], v[216:217], off offset:512
	s_nop 0
	global_load_dwordx4 v[212:215], v[216:217], off offset:576
	s_waitcnt vmcnt(0)
	v_pk_add_f32 v[166:167], v[166:167], 1.0 op_sel_hi:[1,0]
	v_pk_add_f32 v[168:169], v[168:169], 1.0 op_sel_hi:[1,0]
	v_pk_add_f32 v[218:219], v[218:219], 1.0 op_sel_hi:[1,0]
	v_pk_add_f32 v[220:221], v[220:221], 1.0 op_sel_hi:[1,0]
	v_pk_add_f32 v[222:223], v[222:223], 1.0 op_sel_hi:[1,0]
	v_pk_add_f32 v[224:225], v[224:225], 1.0 op_sel_hi:[1,0]
	v_pk_add_f32 v[212:213], v[212:213], 1.0 op_sel_hi:[1,0]
	v_pk_add_f32 v[214:215], v[214:215], 1.0 op_sel_hi:[1,0]
	v_pk_mul_f32 v[58:59], v[58:59], v[166:167]
	v_pk_mul_f32 v[60:61], v[60:61], v[168:169]
	v_pk_mul_f32 v[142:143], v[142:143], v[218:219]
	v_pk_mul_f32 v[144:145], v[144:145], v[220:221]
	v_pk_mul_f32 v[154:155], v[154:155], v[222:223]
	v_pk_mul_f32 v[156:157], v[156:157], v[224:225]
	v_pk_mul_f32 v[158:159], v[158:159], v[212:213]
	v_pk_mul_f32 v[160:161], v[160:161], v[214:215]
	s_branch .LBB0_924
